# mix-GEMM epilogue de-serialised: x loads of 4 row groups in flight, all 16 stores at the end, branchless prompt/sample pointer (on top of attention + PEER U edits)
# speedup vs baseline: 1.0062x; 1.0062x over previous
; __device__ __forceinline__ unsigned cvt_pk_bf16(float lo, float hi) { unsigned r; asm volatile("v_cvt_pk_bf16_f32 %0, %1, %2" : "=v"(r) : "v"(lo), "v"(hi)); return r; }
;     __device__ __forceinline__ void operator()(const f32x4 (&acc)[2][2][4][2], const Unit& u, int wr, int wc, int fr, int fq) const {
;         const int row0 = u.pm * BM + wr * 64 + fr, col0 = u.pn * BM + wc * 32 + 8 * fq;
; #pragma unroll
;         for (int ai = 0; ai < 2; ++ai)
; #pragma unroll
;             for (int m = 0; m < 4; ++m) {
;                 const int row = row0 + ai * HALF + m * 16;
;                 const float* xr = (row < 16384 ? xp + (size_t)row * 4096 : xs + (size_t)(row - 16384) * 4096) + col0;
;                 bf16_t* orow = O + (size_t)row * 4096 + col0;
; #pragma unroll
;                 for (int bj = 0; bj < 2; ++bj) { if (!((u.mask >> (2 * ai + bj)) & 1)) continue;
;                     const f32x4 x0 = *(const f32x4*)(xr + bj * HALF), x1 = *(const f32x4*)(xr + bj * HALF + 4);
;                     const f32x4 v0 = acc[ai][bj][m][0] + alpha * x0, v1 = acc[ai][bj][m][1] + alpha * x1;
;                     u32x4 w; w.x = cvt_pk_bf16(v0[0], v0[1]); w.y = cvt_pk_bf16(v0[2], v0[3]); w.z = cvt_pk_bf16(v1[0], v1[1]); w.w = cvt_pk_bf16(v1[2], v1[3]);
;                     *(u32x4*)(orow + bj * HALF) = w; }
.LBB0_1372:
	v_lshl_add_u32 v144, s24, 8, v150
	v_readlane_b32 s56, v253, 0
	v_readlane_b32 s57, v253, 1
	v_readlane_b32 s58, v253, 2
	v_readlane_b32 s59, v253, 3
	v_cmp_lt_i32_e32 vcc, s48, v144
	v_lshl_or_b32 v146, s22, 8, v152
	v_add_u32_e32 v226, 0xffffc000, v144
	v_ashrrev_i32_e32 v147, 31, v146
	v_mov_b32_e32 v148, s56
	v_mov_b32_e32 v149, s57
	v_mov_b32_e32 v224, s58
	v_mov_b32_e32 v225, s59
	v_cndmask_b32_e32 v226, v144, v226, vcc
	v_cndmask_b32_e32 v148, v148, v224, vcc
	v_cndmask_b32_e32 v149, v149, v225, vcc
	v_mov_b32_e32 v227, 0
	v_mov_b32_e32 v228, v144
	v_mov_b32_e32 v229, 0
	v_lshlrev_b64 v[226:227], 14, v[226:227]
	v_lshlrev_b64 v[228:229], 13, v[228:229]
	v_lshl_add_u64 v[148:149], v[148:149], 0, v[226:227]
	v_lshl_add_u64 v[228:229], s[4:5], 0, v[228:229]
	v_lshl_add_u64 v[148:149], v[146:147], 2, v[148:149]
	v_lshl_add_u64 v[228:229], v[146:147], 1, v[228:229]
	s_mov_b32 s61, 0
	global_load_dwordx4 v[156:159], v[148:149], off
	global_load_dwordx4 v[160:163], v[148:149], off offset:16
	global_load_dwordx4 v[164:167], v[148:149], off offset:512
	global_load_dwordx4 v[168:171], v[148:149], off offset:528
	s_mov_b32 s60, 0x40000
	v_lshl_add_u64 v[224:225], v[148:149], 0, s[60:61]
	global_load_dwordx4 v[172:175], v[224:225], off
	global_load_dwordx4 v[176:179], v[224:225], off offset:16
	global_load_dwordx4 v[180:183], v[224:225], off offset:512
	global_load_dwordx4 v[184:187], v[224:225], off offset:528
	s_mov_b32 s60, 0x80000
	v_lshl_add_u64 v[224:225], v[148:149], 0, s[60:61]
	global_load_dwordx4 v[188:191], v[224:225], off
	global_load_dwordx4 v[192:195], v[224:225], off offset:16
	global_load_dwordx4 v[196:199], v[224:225], off offset:512
	global_load_dwordx4 v[200:203], v[224:225], off offset:528
	s_mov_b32 s60, 0xc0000
	v_lshl_add_u64 v[224:225], v[148:149], 0, s[60:61]
	global_load_dwordx4 v[204:207], v[224:225], off
	global_load_dwordx4 v[208:211], v[224:225], off offset:16
	global_load_dwordx4 v[212:215], v[224:225], off offset:512
	global_load_dwordx4 v[216:219], v[224:225], off offset:528
	s_waitcnt vmcnt(12)
	v_pk_fma_f32 v[124:125], v[156:157], s[10:11], v[124:125] op_sel_hi:[1,0,1]
	v_pk_fma_f32 v[126:127], v[158:159], s[10:11], v[126:127] op_sel_hi:[1,0,1]
	v_pk_fma_f32 v[120:121], v[160:161], s[10:11], v[120:121] op_sel_hi:[1,0,1]
	v_pk_fma_f32 v[122:123], v[162:163], s[10:11], v[122:123] op_sel_hi:[1,0,1]
	v_pk_fma_f32 v[116:117], v[164:165], s[10:11], v[116:117] op_sel_hi:[1,0,1]
	v_pk_fma_f32 v[118:119], v[166:167], s[10:11], v[118:119] op_sel_hi:[1,0,1]
	v_pk_fma_f32 v[112:113], v[168:169], s[10:11], v[112:113] op_sel_hi:[1,0,1]
	v_pk_fma_f32 v[114:115], v[170:171], s[10:11], v[114:115] op_sel_hi:[1,0,1]
	v_cvt_pk_bf16_f32 v124, v124, v125
	v_cvt_pk_bf16_f32 v125, v126, v127
	v_cvt_pk_bf16_f32 v126, v120, v121
	v_cvt_pk_bf16_f32 v127, v122, v123
	v_cvt_pk_bf16_f32 v116, v116, v117
	v_cvt_pk_bf16_f32 v117, v118, v119
	v_cvt_pk_bf16_f32 v118, v112, v113
	v_cvt_pk_bf16_f32 v119, v114, v115
	s_mov_b32 s60, 0x200000
	v_lshl_add_u64 v[224:225], v[148:149], 0, s[60:61]
	global_load_dwordx4 v[156:159], v[224:225], off
	global_load_dwordx4 v[160:163], v[224:225], off offset:16
	global_load_dwordx4 v[164:167], v[224:225], off offset:512
	global_load_dwordx4 v[168:171], v[224:225], off offset:528
	s_waitcnt vmcnt(12)
	v_pk_fma_f32 v[108:109], v[172:173], s[10:11], v[108:109] op_sel_hi:[1,0,1]
	v_pk_fma_f32 v[110:111], v[174:175], s[10:11], v[110:111] op_sel_hi:[1,0,1]
	v_pk_fma_f32 v[104:105], v[176:177], s[10:11], v[104:105] op_sel_hi:[1,0,1]
	v_pk_fma_f32 v[106:107], v[178:179], s[10:11], v[106:107] op_sel_hi:[1,0,1]
	v_pk_fma_f32 v[100:101], v[180:181], s[10:11], v[100:101] op_sel_hi:[1,0,1]
	v_pk_fma_f32 v[102:103], v[182:183], s[10:11], v[102:103] op_sel_hi:[1,0,1]
	v_pk_fma_f32 v[96:97], v[184:185], s[10:11], v[96:97] op_sel_hi:[1,0,1]
	v_pk_fma_f32 v[98:99], v[186:187], s[10:11], v[98:99] op_sel_hi:[1,0,1]
	v_cvt_pk_bf16_f32 v108, v108, v109
	v_cvt_pk_bf16_f32 v109, v110, v111
	v_cvt_pk_bf16_f32 v110, v104, v105
	v_cvt_pk_bf16_f32 v111, v106, v107
	v_cvt_pk_bf16_f32 v100, v100, v101
	v_cvt_pk_bf16_f32 v101, v102, v103
	v_cvt_pk_bf16_f32 v102, v96, v97
	v_cvt_pk_bf16_f32 v103, v98, v99
	s_mov_b32 s60, 0x240000
	v_lshl_add_u64 v[224:225], v[148:149], 0, s[60:61]
	global_load_dwordx4 v[172:175], v[224:225], off
	global_load_dwordx4 v[176:179], v[224:225], off offset:16
	global_load_dwordx4 v[180:183], v[224:225], off offset:512
	global_load_dwordx4 v[184:187], v[224:225], off offset:528
	s_waitcnt vmcnt(12)
	v_pk_fma_f32 v[92:93], v[188:189], s[10:11], v[92:93] op_sel_hi:[1,0,1]
	v_pk_fma_f32 v[94:95], v[190:191], s[10:11], v[94:95] op_sel_hi:[1,0,1]
	v_pk_fma_f32 v[88:89], v[192:193], s[10:11], v[88:89] op_sel_hi:[1,0,1]
	v_pk_fma_f32 v[90:91], v[194:195], s[10:11], v[90:91] op_sel_hi:[1,0,1]
	v_pk_fma_f32 v[84:85], v[196:197], s[10:11], v[84:85] op_sel_hi:[1,0,1]
	v_pk_fma_f32 v[86:87], v[198:199], s[10:11], v[86:87] op_sel_hi:[1,0,1]
	v_pk_fma_f32 v[80:81], v[200:201], s[10:11], v[80:81] op_sel_hi:[1,0,1]
	v_pk_fma_f32 v[82:83], v[202:203], s[10:11], v[82:83] op_sel_hi:[1,0,1]
	v_cvt_pk_bf16_f32 v92, v92, v93
	v_cvt_pk_bf16_f32 v93, v94, v95
	v_cvt_pk_bf16_f32 v94, v88, v89
	v_cvt_pk_bf16_f32 v95, v90, v91
	v_cvt_pk_bf16_f32 v84, v84, v85
	v_cvt_pk_bf16_f32 v85, v86, v87
	v_cvt_pk_bf16_f32 v86, v80, v81
	v_cvt_pk_bf16_f32 v87, v82, v83
	s_mov_b32 s60, 0x280000
	v_lshl_add_u64 v[224:225], v[148:149], 0, s[60:61]
	global_load_dwordx4 v[188:191], v[224:225], off
	global_load_dwordx4 v[192:195], v[224:225], off offset:16
	global_load_dwordx4 v[196:199], v[224:225], off offset:512
	global_load_dwordx4 v[200:203], v[224:225], off offset:528
	s_waitcnt vmcnt(12)
; __device__ __forceinline__ unsigned cvt_pk_bf16(float lo, float hi) { unsigned r; asm volatile("v_cvt_pk_bf16_f32 %0, %1, %2" : "=v"(r) : "v"(lo), "v"(hi)); return r; }
; #define PG8_BAR __builtin_amdgcn_s_barrier()
;     __device__ __forceinline__ void operator()(const f32x4 (&acc)[2][2][4][2], const Unit& u, int wr, int wc, int fr, int fq) const {
;     ...
;             for (int m = 0; m < 4; ++m) {
;                 const int row = row0 + ai * HALF + m * 16;
;                 const float* xr = (row < 16384 ? xp + (size_t)row * 4096 : xs + (size_t)(row - 16384) * 4096) + col0;
;                 bf16_t* orow = O + (size_t)row * 4096 + col0;
; #pragma unroll
;                 for (int bj = 0; bj < 2; ++bj) { if (!((u.mask >> (2 * ai + bj)) & 1)) continue;
;                     const f32x4 x0 = *(const f32x4*)(xr + bj * HALF), x1 = *(const f32x4*)(xr + bj * HALF + 4);
;                     const f32x4 v0 = acc[ai][bj][m][0] + alpha * x0, v1 = acc[ai][bj][m][1] + alpha * x1;
;                     u32x4 w; w.x = cvt_pk_bf16(v0[0], v0[1]); w.y = cvt_pk_bf16(v0[2], v0[3]); w.z = cvt_pk_bf16(v1[0], v1[1]); w.w = cvt_pk_bf16(v1[2], v1[3]);
;                     *(u32x4*)(orow + bj * HALF) = w; }
; template <class Epi, class Sched, bool ALIGN_EPI = false, bool SP2 = false>
; __device__ __forceinline__ void gemm_phase(PG8_LAS unsigned char* lds, const Gemm g, const Sched& S, const Epi& E, int tid_in) {
;     ...
;         if (!has_next) break;
; #pragma unroll
;         for (int a = 0; a < 2; ++a)
; #pragma unroll
;             for (int b = 0; b < 2; ++b)
; #pragma unroll
;                 for (int m = 0; m < 4; ++m)
; #pragma unroll
;                     for (int n = 0; n < 2; ++n) acc[a][b][m][n] = (f32x4){0.f, 0.f, 0.f, 0.f};
;         cur = nxt; cA = nA; cB = nB; ++ui;
;         if constexpr (ALIGN_EPI) { if (wr == 1) PG8_BAR; }
	v_pk_fma_f32 v[76:77], v[204:205], s[10:11], v[76:77] op_sel_hi:[1,0,1]
	v_pk_fma_f32 v[78:79], v[206:207], s[10:11], v[78:79] op_sel_hi:[1,0,1]
	v_pk_fma_f32 v[72:73], v[208:209], s[10:11], v[72:73] op_sel_hi:[1,0,1]
	v_pk_fma_f32 v[74:75], v[210:211], s[10:11], v[74:75] op_sel_hi:[1,0,1]
	v_pk_fma_f32 v[68:69], v[212:213], s[10:11], v[68:69] op_sel_hi:[1,0,1]
	v_pk_fma_f32 v[70:71], v[214:215], s[10:11], v[70:71] op_sel_hi:[1,0,1]
	v_pk_fma_f32 v[64:65], v[216:217], s[10:11], v[64:65] op_sel_hi:[1,0,1]
	v_pk_fma_f32 v[66:67], v[218:219], s[10:11], v[66:67] op_sel_hi:[1,0,1]
	v_cvt_pk_bf16_f32 v76, v76, v77
	v_cvt_pk_bf16_f32 v77, v78, v79
	v_cvt_pk_bf16_f32 v78, v72, v73
	v_cvt_pk_bf16_f32 v79, v74, v75
	v_cvt_pk_bf16_f32 v68, v68, v69
	v_cvt_pk_bf16_f32 v69, v70, v71
	v_cvt_pk_bf16_f32 v70, v64, v65
	v_cvt_pk_bf16_f32 v71, v66, v67
	s_mov_b32 s60, 0x2c0000
	v_lshl_add_u64 v[224:225], v[148:149], 0, s[60:61]
	global_load_dwordx4 v[204:207], v[224:225], off
	global_load_dwordx4 v[208:211], v[224:225], off offset:16
	global_load_dwordx4 v[212:215], v[224:225], off offset:512
	global_load_dwordx4 v[216:219], v[224:225], off offset:528
	s_waitcnt vmcnt(12)
	v_pk_fma_f32 v[60:61], v[156:157], s[10:11], v[60:61] op_sel_hi:[1,0,1]
	v_pk_fma_f32 v[62:63], v[158:159], s[10:11], v[62:63] op_sel_hi:[1,0,1]
	v_pk_fma_f32 v[56:57], v[160:161], s[10:11], v[56:57] op_sel_hi:[1,0,1]
	v_pk_fma_f32 v[58:59], v[162:163], s[10:11], v[58:59] op_sel_hi:[1,0,1]
	v_pk_fma_f32 v[52:53], v[164:165], s[10:11], v[52:53] op_sel_hi:[1,0,1]
	v_pk_fma_f32 v[54:55], v[166:167], s[10:11], v[54:55] op_sel_hi:[1,0,1]
	v_pk_fma_f32 v[48:49], v[168:169], s[10:11], v[48:49] op_sel_hi:[1,0,1]
	v_pk_fma_f32 v[50:51], v[170:171], s[10:11], v[50:51] op_sel_hi:[1,0,1]
	v_cvt_pk_bf16_f32 v60, v60, v61
	v_cvt_pk_bf16_f32 v61, v62, v63
	v_cvt_pk_bf16_f32 v62, v56, v57
	v_cvt_pk_bf16_f32 v63, v58, v59
	v_cvt_pk_bf16_f32 v52, v52, v53
	v_cvt_pk_bf16_f32 v53, v54, v55
	v_cvt_pk_bf16_f32 v54, v48, v49
	v_cvt_pk_bf16_f32 v55, v50, v51
	s_waitcnt vmcnt(8)
	v_pk_fma_f32 v[44:45], v[172:173], s[10:11], v[44:45] op_sel_hi:[1,0,1]
	v_pk_fma_f32 v[46:47], v[174:175], s[10:11], v[46:47] op_sel_hi:[1,0,1]
	v_pk_fma_f32 v[40:41], v[176:177], s[10:11], v[40:41] op_sel_hi:[1,0,1]
	v_pk_fma_f32 v[42:43], v[178:179], s[10:11], v[42:43] op_sel_hi:[1,0,1]
	v_pk_fma_f32 v[36:37], v[180:181], s[10:11], v[36:37] op_sel_hi:[1,0,1]
	v_pk_fma_f32 v[38:39], v[182:183], s[10:11], v[38:39] op_sel_hi:[1,0,1]
	v_pk_fma_f32 v[32:33], v[184:185], s[10:11], v[32:33] op_sel_hi:[1,0,1]
	v_pk_fma_f32 v[34:35], v[186:187], s[10:11], v[34:35] op_sel_hi:[1,0,1]
	v_cvt_pk_bf16_f32 v44, v44, v45
	v_cvt_pk_bf16_f32 v45, v46, v47
	v_cvt_pk_bf16_f32 v46, v40, v41
	v_cvt_pk_bf16_f32 v47, v42, v43
	v_cvt_pk_bf16_f32 v36, v36, v37
	v_cvt_pk_bf16_f32 v37, v38, v39
	v_cvt_pk_bf16_f32 v38, v32, v33
	v_cvt_pk_bf16_f32 v39, v34, v35
	s_waitcnt vmcnt(4)
	v_pk_fma_f32 v[28:29], v[188:189], s[10:11], v[28:29] op_sel_hi:[1,0,1]
	v_pk_fma_f32 v[30:31], v[190:191], s[10:11], v[30:31] op_sel_hi:[1,0,1]
	v_pk_fma_f32 v[24:25], v[192:193], s[10:11], v[24:25] op_sel_hi:[1,0,1]
	v_pk_fma_f32 v[26:27], v[194:195], s[10:11], v[26:27] op_sel_hi:[1,0,1]
	v_pk_fma_f32 v[20:21], v[196:197], s[10:11], v[20:21] op_sel_hi:[1,0,1]
	v_pk_fma_f32 v[22:23], v[198:199], s[10:11], v[22:23] op_sel_hi:[1,0,1]
	v_pk_fma_f32 v[16:17], v[200:201], s[10:11], v[16:17] op_sel_hi:[1,0,1]
	v_pk_fma_f32 v[18:19], v[202:203], s[10:11], v[18:19] op_sel_hi:[1,0,1]
	v_cvt_pk_bf16_f32 v28, v28, v29
	v_cvt_pk_bf16_f32 v29, v30, v31
	v_cvt_pk_bf16_f32 v30, v24, v25
	v_cvt_pk_bf16_f32 v31, v26, v27
	v_cvt_pk_bf16_f32 v20, v20, v21
	v_cvt_pk_bf16_f32 v21, v22, v23
	v_cvt_pk_bf16_f32 v22, v16, v17
	v_cvt_pk_bf16_f32 v23, v18, v19
	s_waitcnt vmcnt(0)
	v_pk_fma_f32 v[12:13], v[204:205], s[10:11], v[12:13] op_sel_hi:[1,0,1]
	v_pk_fma_f32 v[14:15], v[206:207], s[10:11], v[14:15] op_sel_hi:[1,0,1]
	v_pk_fma_f32 v[8:9], v[208:209], s[10:11], v[8:9] op_sel_hi:[1,0,1]
	v_pk_fma_f32 v[10:11], v[210:211], s[10:11], v[10:11] op_sel_hi:[1,0,1]
	v_pk_fma_f32 v[4:5], v[212:213], s[10:11], v[4:5] op_sel_hi:[1,0,1]
	v_pk_fma_f32 v[6:7], v[214:215], s[10:11], v[6:7] op_sel_hi:[1,0,1]
	v_pk_fma_f32 v[0:1], v[216:217], s[10:11], v[0:1] op_sel_hi:[1,0,1]
	v_pk_fma_f32 v[2:3], v[218:219], s[10:11], v[2:3] op_sel_hi:[1,0,1]
	v_cvt_pk_bf16_f32 v12, v12, v13
	v_cvt_pk_bf16_f32 v13, v14, v15
	v_cvt_pk_bf16_f32 v14, v8, v9
	v_cvt_pk_bf16_f32 v15, v10, v11
	v_cvt_pk_bf16_f32 v4, v4, v5
	v_cvt_pk_bf16_f32 v5, v6, v7
	v_cvt_pk_bf16_f32 v6, v0, v1
	v_cvt_pk_bf16_f32 v7, v2, v3
	global_store_dwordx4 v[228:229], v[124:127], off
	global_store_dwordx4 v[228:229], v[116:119], off offset:256
	s_mov_b32 s60, 0x20000
	v_lshl_add_u64 v[224:225], v[228:229], 0, s[60:61]
	global_store_dwordx4 v[224:225], v[108:111], off
	global_store_dwordx4 v[224:225], v[100:103], off offset:256
	s_mov_b32 s60, 0x40000
	v_lshl_add_u64 v[224:225], v[228:229], 0, s[60:61]
	global_store_dwordx4 v[224:225], v[92:95], off
	global_store_dwordx4 v[224:225], v[84:87], off offset:256
	s_mov_b32 s60, 0x60000
	v_lshl_add_u64 v[224:225], v[228:229], 0, s[60:61]
	global_store_dwordx4 v[224:225], v[76:79], off
	global_store_dwordx4 v[224:225], v[68:71], off offset:256
	s_mov_b32 s60, 0x100000
	v_lshl_add_u64 v[224:225], v[228:229], 0, s[60:61]
	global_store_dwordx4 v[224:225], v[60:63], off
	global_store_dwordx4 v[224:225], v[52:55], off offset:256
	s_mov_b32 s60, 0x120000
	v_lshl_add_u64 v[224:225], v[228:229], 0, s[60:61]
	global_store_dwordx4 v[224:225], v[44:47], off
	global_store_dwordx4 v[224:225], v[36:39], off offset:256
	s_mov_b32 s60, 0x140000
	v_lshl_add_u64 v[224:225], v[228:229], 0, s[60:61]
	global_store_dwordx4 v[224:225], v[28:31], off
	global_store_dwordx4 v[224:225], v[20:23], off offset:256
	s_mov_b32 s60, 0x160000
	v_lshl_add_u64 v[224:225], v[228:229], 0, s[60:61]
	global_store_dwordx4 v[224:225], v[12:15], off
	global_store_dwordx4 v[224:225], v[4:7], off offset:256
	s_andn2_b64 vcc, exec, s[18:19]
	s_mov_b64 s[18:19], -1
	s_nop 1
	s_cbranch_vccnz .LBB0_1364
	s_andn2_b64 vcc, exec, s[0:1]
	s_cbranch_vccnz .LBB0_1363
	s_barrier
	s_branch .LBB0_1363
